# sc1 write-through scope on the prologue streaming stores (bf16 weight copies, HB, MEMN), on top of v11
# speedup vs baseline: 1.0023x; 1.0010x over previous
; #define LAS __attribute__((address_space(3)))
; __device__ __forceinline__ unsigned pk2(float lo, float hi) { const f32x2v v = {lo, hi}; return __builtin_bit_cast(unsigned, __builtin_convertvector(v, bf16x2v)); }
; __device__ __forceinline__ void tr_item(const float* W, int N, bf16_t* WT, int item, int lane, LAS float* scr, int fox, const float* gk) {
;     const int nblk = (N + 31) >> 5, kb = item / nblk, nb = item - kb * nblk, k0 = 64 * kb, n0 = 32 * nb;
;     const int nq = lane & 7, kr = lane >> 3, nc = n0 + 4 * nq;
;     f32x4 wv[8];
; #pragma unroll
;     for (int i = 0; i < 8; ++i) wv[i] = (nc < N) ? *(const f32x4*)(W + (size_t)(k0 + kr + 8 * i) * N + nc) : (f32x4){0.f, 0.f, 0.f, 0.f};
; #pragma unroll
;     for (int i = 0; i < 8; ++i) { const int kk = kr + 8 * i; const float gg = gk ? gk[k0 + kk] : 1.f;
; #pragma unroll
;         for (int e2 = 0; e2 < 4; ++e2) scr[kk * 33 + 4 * nq + e2] = wv[i][e2] * gg; }
;     asm volatile("s_waitcnt lgkmcnt(0)" ::: "memory");
;     const int c = lane & 7;
; #pragma unroll
;     for (int j = 0; j < 4; ++j) { const int nl = (lane >> 3) + 8 * j, n = n0 + nl; const LAS float* s = scr + (8 * c) * 33 + nl;
;         if (n < N) { int nd = n; if (fox) { if (n >= 4620) nd = n - 12; else if (n >= 4608) nd = n - 4608 + 7168; }
;             u32x4 o; o.x = pk2(s[0 * 33], s[1 * 33]); o.y = pk2(s[2 * 33], s[3 * 33]); o.z = pk2(s[4 * 33], s[5 * 33]); o.w = pk2(s[6 * 33], s[7 * 33]);
;             *(u32x4*)(WT + (size_t)nd * DM + k0 + 8 * c) = o; } }
;     asm volatile("s_waitcnt lgkmcnt(0)" ::: "memory");
.LBB0_646:
	s_add_i32 s13, s7, 0x8420
	s_cmpk_gt_i32 s13, 0x15ff
	s_mov_b64 s[0:1], -1
	s_cbranch_scc0 .LBB0_736
	s_cmpk_gt_u32 s13, 0x321f
	s_cbranch_scc0 .LBB0_709
	s_cmpk_gt_u32 s13, 0x4e1f
	s_cbranch_scc0 .LBB0_682
	s_cmpk_gt_u32 s13, 0x641f
	s_cbranch_scc0 .LBB0_655
	s_cmpk_gt_u32 s13, 0x841f
	s_cbranch_scc0 .LBB0_652
	v_readlane_b32 s0, v252, 33
	v_readlane_b32 s1, v252, 34
	s_mov_b32 s15, s1
	s_lshr_b32 s14, s7, 10
	s_lshl_b64 s[0:1], s[14:15], 23
	s_add_u32 s4, s46, s0
	s_addc_u32 s5, s47, s1
	s_mov_b32 s1, s15
	v_writelane_b32 v252, s0, 33
	v_add_u32_e32 v46, v50, v51
	v_add_u32_e32 v47, 0x420, v46
	v_writelane_b32 v252, s1, 34
	s_lshl_b64 s[0:1], s[14:15], 22
	v_readlane_b32 s14, v250, 3
	v_readlane_b32 s15, v250, 4
	s_add_u32 s14, s14, s0
	s_addc_u32 s1, s15, s1
	s_and_b32 s0, s9, 0x3e0
	s_and_b32 s15, s8, 0x7c0
	v_or_b32_e32 v0, s0, v37
	v_or_b32_e32 v4, s15, v34
	v_lshlrev_b32_e32 v0, 2, v0
	v_lshl_add_u64 v[2:3], s[4:5], 0, v[0:1]
	v_lshlrev_b32_e32 v0, 12, v4
	v_lshl_add_u64 v[30:31], v[2:3], 0, v[0:1]
	s_mov_b32 s4, 0x8000
	v_add_co_u32_e32 v6, vcc, s4, v30
	s_mov_b32 s4, 0x10000
	s_nop 0
	v_addc_co_u32_e32 v7, vcc, 0, v31, vcc
	v_add_co_u32_e32 v10, vcc, s4, v30
	s_mov_b32 s4, 0x18000
	s_nop 0
	v_addc_co_u32_e32 v11, vcc, 0, v31, vcc
	v_add_co_u32_e32 v14, vcc, s4, v30
	s_mov_b32 s4, 0x20000
	s_nop 0
	v_addc_co_u32_e32 v15, vcc, 0, v31, vcc
	v_add_co_u32_e32 v18, vcc, s4, v30
	s_mov_b32 s4, 0x28000
	s_nop 0
	v_addc_co_u32_e32 v19, vcc, 0, v31, vcc
	v_add_co_u32_e32 v22, vcc, s4, v30
	global_load_dwordx4 v[2:5], v[30:31], off
	s_nop 0
	global_load_dwordx4 v[6:9], v[6:7], off
	v_addc_co_u32_e32 v23, vcc, 0, v31, vcc
	global_load_dwordx4 v[10:13], v[10:11], off
	s_nop 0
	global_load_dwordx4 v[14:17], v[14:15], off
	s_nop 0
	global_load_dwordx4 v[18:21], v[18:19], off
	s_nop 0
	global_load_dwordx4 v[22:25], v[22:23], off
	s_mov_b32 s4, 0x30000
	v_add_co_u32_e32 v26, vcc, s4, v30
	s_mov_b32 s4, 0x38000
	s_nop 0
	v_addc_co_u32_e32 v27, vcc, 0, v31, vcc
	global_load_dwordx4 v[26:29], v[26:27], off
	v_add_co_u32_e32 v30, vcc, s4, v30
	v_add_u32_e32 v48, 0x428, v46
	s_nop 0
	v_addc_co_u32_e32 v31, vcc, 0, v31, vcc
	global_load_dwordx4 v[30:33], v[30:31], off
	v_add_u32_e32 v49, 0x840, v46
	v_add_u32_e32 v84, 0x848, v46
	v_add_u32_e32 v85, 0xc60, v46
	v_add_u32_e32 v86, 0xc68, v46
	v_add_u32_e32 v87, 0x1080, v46
	v_add_u32_e32 v88, 0x1088, v46
	v_add_u32_e32 v89, 0x14a0, v46
	v_add_u32_e32 v90, 0x14a8, v46
	v_add_u32_e32 v91, 0x18c0, v46
	v_add_u32_e32 v92, 0x18c8, v46
	v_add_u32_e32 v93, 0x1ce0, v46
	v_add_u32_e32 v94, 0x1ce8, v46
	s_lshl_b32 s4, s15, 1
	s_add_u32 s4, s14, s4
	v_or_b32_e32 v95, s0, v34
	s_addc_u32 s5, s1, 0
	v_lshlrev_b32_e32 v0, 1, v36
	s_waitcnt vmcnt(0)
	ds_write2_b32 v46, v2, v3 offset1:1
	ds_write2_b32 v46, v4, v5 offset0:2 offset1:3
	ds_write2_b32 v47, v6, v7 offset1:1
	ds_write2_b32 v48, v8, v9 offset1:1
	ds_write2_b32 v49, v10, v11 offset1:1
	ds_write2_b32 v84, v12, v13 offset1:1
	ds_write2_b32 v85, v14, v15 offset1:1
	ds_write2_b32 v86, v16, v17 offset1:1
	ds_write2_b32 v87, v18, v19 offset1:1
	ds_write2_b32 v88, v20, v21 offset1:1
	ds_write2_b32 v89, v22, v23 offset1:1
	ds_write2_b32 v90, v24, v25 offset1:1
	ds_write2_b32 v91, v26, v27 offset1:1
	ds_write2_b32 v92, v28, v29 offset1:1
	ds_write2_b32 v93, v30, v31 offset1:1
	ds_write2_b32 v94, v32, v33 offset1:1
	s_waitcnt lgkmcnt(0)
	ds_read_b32 v2, v55
	ds_read_b32 v3, v55 offset:132
	ds_read_b32 v4, v55 offset:264
	ds_read_b32 v5, v55 offset:396
	ds_read_b32 v8, v55 offset:528
	ds_read_b32 v9, v55 offset:660
	ds_read_b32 v10, v55 offset:792
	ds_read_b32 v11, v55 offset:924
	v_lshl_add_u64 v[6:7], s[4:5], 0, v[0:1]
	v_lshlrev_b32_e32 v0, 12, v95
	s_waitcnt lgkmcnt(0)
	v_cvt_pk_bf16_f32 v2, v2, v3
	s_waitcnt lgkmcnt(4)
	v_cvt_pk_bf16_f32 v3, v4, v5
	s_waitcnt lgkmcnt(2)
	v_cvt_pk_bf16_f32 v4, v8, v9
	s_waitcnt lgkmcnt(0)
	v_cvt_pk_bf16_f32 v5, v10, v11
	v_lshl_add_u64 v[8:9], v[6:7], 0, v[0:1]
	global_store_dwordx4 v[8:9], v[2:5], off sc1
	ds_read_b32 v0, v55 offset:32
	ds_read_b32 v2, v55 offset:164
	ds_read_b32 v3, v55 offset:296
	ds_read_b32 v4, v55 offset:428
	ds_read_b32 v5, v55 offset:560
	ds_read_b32 v8, v55 offset:692
	ds_read_b32 v9, v55 offset:824
	ds_read_b32 v10, v55 offset:956
	v_or_b32_e32 v11, s0, v52
	s_waitcnt lgkmcnt(0)
	v_cvt_pk_bf16_f32 v2, v0, v2
	v_lshlrev_b32_e32 v0, 12, v11
	v_cvt_pk_bf16_f32 v3, v3, v4
	v_cvt_pk_bf16_f32 v4, v5, v8
	v_cvt_pk_bf16_f32 v5, v9, v10
	v_lshl_add_u64 v[8:9], v[6:7], 0, v[0:1]
	global_store_dwordx4 v[8:9], v[2:5], off sc1
	ds_read_b32 v0, v55 offset:64
	ds_read_b32 v2, v55 offset:196
	ds_read_b32 v3, v55 offset:328
	ds_read_b32 v4, v55 offset:460
	ds_read_b32 v5, v55 offset:592
	ds_read_b32 v8, v55 offset:724
	ds_read_b32 v9, v55 offset:856
	ds_read_b32 v10, v55 offset:988
	v_or_b32_e32 v11, s0, v53
	s_waitcnt lgkmcnt(0)
	v_cvt_pk_bf16_f32 v2, v0, v2
	v_lshlrev_b32_e32 v0, 12, v11
	v_cvt_pk_bf16_f32 v3, v3, v4
	v_cvt_pk_bf16_f32 v4, v5, v8
	v_cvt_pk_bf16_f32 v5, v9, v10
	v_lshl_add_u64 v[8:9], v[6:7], 0, v[0:1]
	global_store_dwordx4 v[8:9], v[2:5], off sc1
	ds_read_b32 v0, v55 offset:96
	ds_read_b32 v2, v55 offset:228
	ds_read_b32 v3, v55 offset:360
	ds_read_b32 v4, v55 offset:492
	ds_read_b32 v5, v55 offset:624
	ds_read_b32 v8, v55 offset:756
	ds_read_b32 v9, v55 offset:888
	ds_read_b32 v10, v55 offset:1020
	v_or_b32_e32 v11, s0, v54
	s_waitcnt lgkmcnt(0)
	v_cvt_pk_bf16_f32 v2, v0, v2
	v_lshlrev_b32_e32 v0, 12, v11
	v_cvt_pk_bf16_f32 v3, v3, v4
	v_cvt_pk_bf16_f32 v4, v5, v8
	v_cvt_pk_bf16_f32 v5, v9, v10
	v_lshl_add_u64 v[6:7], v[6:7], 0, v[0:1]
	global_store_dwordx4 v[6:7], v[2:5], off sc1
	s_waitcnt lgkmcnt(0)
	s_mov_b64 s[0:1], 0
; #define LAS __attribute__((address_space(3)))
; __device__ __forceinline__ unsigned pk2(float lo, float hi) { const f32x2v v = {lo, hi}; return __builtin_bit_cast(unsigned, __builtin_convertvector(v, bf16x2v)); }
; __device__ __forceinline__ void tr_item(const float* W, int N, bf16_t* WT, int item, int lane, LAS float* scr, int fox, const float* gk) {
;     const int nblk = (N + 31) >> 5, kb = item / nblk, nb = item - kb * nblk, k0 = 64 * kb, n0 = 32 * nb;
;     const int nq = lane & 7, kr = lane >> 3, nc = n0 + 4 * nq;
;     f32x4 wv[8];
; #pragma unroll
;     for (int i = 0; i < 8; ++i) wv[i] = (nc < N) ? *(const f32x4*)(W + (size_t)(k0 + kr + 8 * i) * N + nc) : (f32x4){0.f, 0.f, 0.f, 0.f};
; #pragma unroll
;     for (int i = 0; i < 8; ++i) { const int kk = kr + 8 * i; const float gg = gk ? gk[k0 + kk] : 1.f;
; #pragma unroll
;         for (int e2 = 0; e2 < 4; ++e2) scr[kk * 33 + 4 * nq + e2] = wv[i][e2] * gg; }
;     asm volatile("s_waitcnt lgkmcnt(0)" ::: "memory");
;     const int c = lane & 7;
; #pragma unroll
;     for (int j = 0; j < 4; ++j) { const int nl = (lane >> 3) + 8 * j, n = n0 + nl; const LAS float* s = scr + (8 * c) * 33 + nl;
;         if (n < N) { int nd = n; if (fox) { if (n >= 4620) nd = n - 12; else if (n >= 4608) nd = n - 4608 + 7168; }
;             u32x4 o; o.x = pk2(s[0 * 33], s[1 * 33]); o.y = pk2(s[2 * 33], s[3 * 33]); o.z = pk2(s[4 * 33], s[5 * 33]); o.w = pk2(s[6 * 33], s[7 * 33]);
;             *(u32x4*)(WT + (size_t)nd * DM + k0 + 8 * c) = o; } }
;     asm volatile("s_waitcnt lgkmcnt(0)" ::: "memory");
.LBB0_652:
	s_andn2_b64 vcc, exec, s[0:1]
	s_cbranch_vccnz .LBB0_654
	v_readlane_b32 s0, v252, 33
	s_add_i32 s14, s7, 0x2000
	v_readlane_b32 s1, v252, 34
	s_mov_b32 s17, s1
	s_and_b32 s16, s14, 0xfffff800
	s_lshl_b64 s[0:1], s[16:17], 13
	v_readlane_b32 s72, v251, 22
	v_readlane_b32 s73, v251, 23
	s_add_u32 s4, s72, s0
	s_addc_u32 s5, s73, s1
	s_mov_b32 s1, s17
	v_writelane_b32 v252, s0, 33
	v_readlane_b32 s15, v250, 1
	v_add_u32_e32 v46, v50, v51
	v_writelane_b32 v252, s1, 34
	s_lshl_b64 s[0:1], s[16:17], 12
	s_add_u32 s15, s15, s0
	v_readlane_b32 s0, v250, 2
	s_addc_u32 s1, s0, s1
	s_add_i32 s0, s9, 0xfff37c00
	s_and_b32 s0, s0, 0x7e0
	s_and_b32 s14, s14, 0x7c0
	v_or_b32_e32 v0, s0, v37
	v_or_b32_e32 v4, s14, v34
	v_lshlrev_b32_e32 v0, 2, v0
	v_lshl_add_u64 v[2:3], s[4:5], 0, v[0:1]
	v_lshlrev_b32_e32 v0, 13, v4
	v_lshl_add_u64 v[30:31], v[2:3], 0, v[0:1]
	s_mov_b32 s4, 0x10000
	v_add_co_u32_e32 v6, vcc, s4, v30
	s_mov_b32 s4, 0x20000
	s_nop 0
	v_addc_co_u32_e32 v7, vcc, 0, v31, vcc
	v_add_co_u32_e32 v10, vcc, s4, v30
	s_mov_b32 s4, 0x30000
	s_nop 0
	v_addc_co_u32_e32 v11, vcc, 0, v31, vcc
	v_add_co_u32_e32 v14, vcc, s4, v30
	s_mov_b32 s4, 0x40000
	s_nop 0
	v_addc_co_u32_e32 v15, vcc, 0, v31, vcc
	v_add_co_u32_e32 v18, vcc, s4, v30
	s_mov_b32 s4, 0x50000
	s_nop 0
	v_addc_co_u32_e32 v19, vcc, 0, v31, vcc
	v_add_co_u32_e32 v22, vcc, s4, v30
	global_load_dwordx4 v[2:5], v[30:31], off
	s_nop 0
	global_load_dwordx4 v[6:9], v[6:7], off
	v_addc_co_u32_e32 v23, vcc, 0, v31, vcc
	global_load_dwordx4 v[10:13], v[10:11], off
	s_nop 0
	global_load_dwordx4 v[14:17], v[14:15], off
	s_nop 0
	global_load_dwordx4 v[18:21], v[18:19], off
	s_nop 0
	global_load_dwordx4 v[22:25], v[22:23], off
	s_mov_b32 s4, 0x60000
	v_add_co_u32_e32 v26, vcc, s4, v30
	s_mov_b32 s4, 0x70000
	s_nop 0
	v_addc_co_u32_e32 v27, vcc, 0, v31, vcc
	global_load_dwordx4 v[26:29], v[26:27], off
	v_add_co_u32_e32 v30, vcc, s4, v30
	v_add_u32_e32 v47, 0x420, v46
	s_nop 0
	v_addc_co_u32_e32 v31, vcc, 0, v31, vcc
	global_load_dwordx4 v[30:33], v[30:31], off
	v_add_u32_e32 v48, 0x428, v46
	v_add_u32_e32 v49, 0x840, v46
	v_add_u32_e32 v84, 0x848, v46
	v_add_u32_e32 v85, 0xc60, v46
	v_add_u32_e32 v86, 0xc68, v46
	v_add_u32_e32 v87, 0x1080, v46
	v_add_u32_e32 v88, 0x1088, v46
	v_add_u32_e32 v89, 0x14a0, v46
	v_add_u32_e32 v90, 0x14a8, v46
	v_add_u32_e32 v91, 0x18c0, v46
	v_add_u32_e32 v92, 0x18c8, v46
	v_add_u32_e32 v93, 0x1ce0, v46
	v_add_u32_e32 v94, 0x1ce8, v46
	s_lshl_b32 s4, s14, 1
	s_add_u32 s4, s15, s4
	v_or_b32_e32 v95, s0, v34
	s_addc_u32 s5, s1, 0
	v_lshlrev_b32_e32 v0, 1, v36
	v_readlane_b32 s74, v251, 24
	v_readlane_b32 s75, v251, 25
	v_readlane_b32 s76, v251, 26
	v_readlane_b32 s77, v251, 27
	v_readlane_b32 s78, v251, 28
	v_readlane_b32 s79, v251, 29
	v_readlane_b32 s80, v251, 30
	v_readlane_b32 s81, v251, 31
	v_readlane_b32 s82, v251, 32
	v_readlane_b32 s83, v251, 33
	v_readlane_b32 s84, v251, 34
	v_readlane_b32 s85, v251, 35
	v_readlane_b32 s86, v251, 36
	v_readlane_b32 s87, v251, 37
	s_waitcnt vmcnt(0)
	ds_write2_b32 v46, v2, v3 offset1:1
	ds_write2_b32 v46, v4, v5 offset0:2 offset1:3
	ds_write2_b32 v47, v6, v7 offset1:1
	ds_write2_b32 v48, v8, v9 offset1:1
	ds_write2_b32 v49, v10, v11 offset1:1
	ds_write2_b32 v84, v12, v13 offset1:1
	ds_write2_b32 v85, v14, v15 offset1:1
	ds_write2_b32 v86, v16, v17 offset1:1
	ds_write2_b32 v87, v18, v19 offset1:1
	ds_write2_b32 v88, v20, v21 offset1:1
	ds_write2_b32 v89, v22, v23 offset1:1
	ds_write2_b32 v90, v24, v25 offset1:1
	ds_write2_b32 v91, v26, v27 offset1:1
	ds_write2_b32 v92, v28, v29 offset1:1
	ds_write2_b32 v93, v30, v31 offset1:1
	ds_write2_b32 v94, v32, v33 offset1:1
	s_waitcnt lgkmcnt(0)
	ds_read_b32 v2, v55
	ds_read_b32 v3, v55 offset:132
	ds_read_b32 v4, v55 offset:264
	ds_read_b32 v5, v55 offset:396
	ds_read_b32 v8, v55 offset:528
	ds_read_b32 v9, v55 offset:660
	ds_read_b32 v10, v55 offset:792
	ds_read_b32 v11, v55 offset:924
	v_lshl_add_u64 v[6:7], s[4:5], 0, v[0:1]
	v_lshlrev_b32_e32 v0, 12, v95
	s_waitcnt lgkmcnt(0)
	v_cvt_pk_bf16_f32 v2, v2, v3
	v_cvt_pk_bf16_f32 v3, v4, v5
	v_cvt_pk_bf16_f32 v4, v8, v9
	v_cvt_pk_bf16_f32 v5, v10, v11
	v_lshl_add_u64 v[8:9], v[6:7], 0, v[0:1]
	global_store_dwordx4 v[8:9], v[2:5], off sc1
	ds_read_b32 v0, v55 offset:32
	ds_read_b32 v2, v55 offset:164
	ds_read_b32 v3, v55 offset:296
	ds_read_b32 v4, v55 offset:428
	ds_read_b32 v5, v55 offset:560
	ds_read_b32 v8, v55 offset:692
	ds_read_b32 v9, v55 offset:824
	ds_read_b32 v10, v55 offset:956
	v_or_b32_e32 v11, s0, v52
	s_waitcnt lgkmcnt(0)
	v_cvt_pk_bf16_f32 v2, v0, v2
	v_lshlrev_b32_e32 v0, 12, v11
	v_cvt_pk_bf16_f32 v3, v3, v4
	v_cvt_pk_bf16_f32 v4, v5, v8
	v_cvt_pk_bf16_f32 v5, v9, v10
	v_lshl_add_u64 v[8:9], v[6:7], 0, v[0:1]
	global_store_dwordx4 v[8:9], v[2:5], off sc1
	ds_read_b32 v0, v55 offset:64
	ds_read_b32 v2, v55 offset:196
	ds_read_b32 v3, v55 offset:328
	ds_read_b32 v4, v55 offset:460
	ds_read_b32 v5, v55 offset:592
	ds_read_b32 v8, v55 offset:724
	ds_read_b32 v9, v55 offset:856
	ds_read_b32 v10, v55 offset:988
	v_or_b32_e32 v11, s0, v53
	s_waitcnt lgkmcnt(0)
	v_cvt_pk_bf16_f32 v2, v0, v2
	v_lshlrev_b32_e32 v0, 12, v11
	v_cvt_pk_bf16_f32 v3, v3, v4
	v_cvt_pk_bf16_f32 v4, v5, v8
	v_cvt_pk_bf16_f32 v5, v9, v10
	v_lshl_add_u64 v[8:9], v[6:7], 0, v[0:1]
	global_store_dwordx4 v[8:9], v[2:5], off sc1
	ds_read_b32 v0, v55 offset:96
	ds_read_b32 v2, v55 offset:228
	ds_read_b32 v3, v55 offset:360
	ds_read_b32 v4, v55 offset:492
	ds_read_b32 v5, v55 offset:624
	ds_read_b32 v8, v55 offset:756
	ds_read_b32 v9, v55 offset:888
	ds_read_b32 v10, v55 offset:1020
	v_or_b32_e32 v11, s0, v54
	s_waitcnt lgkmcnt(0)
	v_cvt_pk_bf16_f32 v2, v0, v2
	v_lshlrev_b32_e32 v0, 12, v11
	v_cvt_pk_bf16_f32 v3, v3, v4
	v_cvt_pk_bf16_f32 v4, v5, v8
	v_cvt_pk_bf16_f32 v5, v9, v10
	v_lshl_add_u64 v[6:7], v[6:7], 0, v[0:1]
	global_store_dwordx4 v[6:7], v[2:5], off sc1
	s_waitcnt lgkmcnt(0)

; #define LAS __attribute__((address_space(3)))
; __device__ __forceinline__ unsigned pk2(float lo, float hi) { const f32x2v v = {lo, hi}; return __builtin_bit_cast(unsigned, __builtin_convertvector(v, bf16x2v)); }
; __device__ __forceinline__ void tr_item(const float* W, int N, bf16_t* WT, int item, int lane, LAS float* scr, int fox, const float* gk) {
;     const int nblk = (N + 31) >> 5, kb = item / nblk, nb = item - kb * nblk, k0 = 64 * kb, n0 = 32 * nb;
;     const int nq = lane & 7, kr = lane >> 3, nc = n0 + 4 * nq;
;     f32x4 wv[8];
; #pragma unroll
;     for (int i = 0; i < 8; ++i) wv[i] = (nc < N) ? *(const f32x4*)(W + (size_t)(k0 + kr + 8 * i) * N + nc) : (f32x4){0.f, 0.f, 0.f, 0.f};
; #pragma unroll
;     for (int i = 0; i < 8; ++i) { const int kk = kr + 8 * i; const float gg = gk ? gk[k0 + kk] : 1.f;
; #pragma unroll
;         for (int e2 = 0; e2 < 4; ++e2) scr[kk * 33 + 4 * nq + e2] = wv[i][e2] * gg; }
;     asm volatile("s_waitcnt lgkmcnt(0)" ::: "memory");
;     const int c = lane & 7;
; #pragma unroll
;     for (int j = 0; j < 4; ++j) { const int nl = (lane >> 3) + 8 * j, n = n0 + nl; const LAS float* s = scr + (8 * c) * 33 + nl;
;         if (n < N) { int nd = n; if (fox) { if (n >= 4620) nd = n - 12; else if (n >= 4608) nd = n - 4608 + 7168; }
;             u32x4 o; o.x = pk2(s[0 * 33], s[1 * 33]); o.y = pk2(s[2 * 33], s[3 * 33]); o.z = pk2(s[4 * 33], s[5 * 33]); o.w = pk2(s[6 * 33], s[7 * 33]);
;             *(u32x4*)(WT + (size_t)nd * DM + k0 + 8 * c) = o; } }
;     asm volatile("s_waitcnt lgkmcnt(0)" ::: "memory");
.LBB0_672:
	s_or_b64 exec, exec, s[4:5]
	v_lshlrev_b32_e32 v0, 2, v48
	v_readlane_b32 s0, v252, 16
	v_or_b32_e32 v46, s15, v52
	v_or_b32_e32 v47, s15, v53
	v_or_b32_e32 v48, s15, v54
	v_readlane_b32 s1, v252, 17
	v_lshlrev_b32_e32 v46, 2, v46
	v_lshlrev_b32_e32 v47, 2, v47
	v_lshlrev_b32_e32 v49, 2, v48
	v_or_b32_e32 v48, s15, v56
	v_lshlrev_b32_e32 v85, 2, v48
	global_load_dword v0, v0, s[0:1]
	s_nop 0
	global_load_dword v46, v46, s[0:1]
	s_nop 0
	global_load_dword v48, v47, s[0:1]
	global_load_dword v84, v49, s[0:1]
	global_load_dword v86, v85, s[0:1]
	v_or_b32_e32 v47, s15, v58
	v_lshlrev_b32_e32 v47, 2, v47
	v_or_b32_e32 v49, s15, v59
	v_lshlrev_b32_e32 v49, 2, v49
	global_load_dword v88, v47, s[0:1]
	global_load_dword v90, v49, s[0:1]
	v_or_b32_e32 v47, s15, v60
	v_lshlrev_b32_e32 v47, 2, v47
	global_load_dword v92, v47, s[0:1]
	v_add_u32_e32 v47, v50, v51
	v_add_u32_e32 v49, v50, v57
	v_add_u32_e32 v85, 0x420, v47
	v_add_u32_e32 v87, 0x428, v47
	v_add_u32_e32 v89, 0x840, v47
	v_add_u32_e32 v91, 0x848, v47
	v_add_u32_e32 v93, 0xc60, v47
	v_add_u32_e32 v94, 0xc68, v47
	v_add_u32_e32 v95, 0x420, v49
	v_add_u32_e32 v96, 0x428, v49
	v_add_u32_e32 v97, 0x840, v49
	v_add_u32_e32 v98, 0x848, v49
	v_add_u32_e32 v99, 0xc60, v49
	v_add_u32_e32 v100, 0xc68, v49
	v_readlane_b32 s0, v252, 33
	v_readlane_b32 s1, v252, 34
	s_mov_b32 s5, s1
	s_lshl_b32 s4, s15, 1
	v_writelane_b32 v252, s0, 33
	s_waitcnt vmcnt(0)
	v_pk_mul_f32 v[10:11], v[10:11], v[84:85] op_sel_hi:[1,0]
	v_pk_mul_f32 v[2:3], v[2:3], v[0:1] op_sel_hi:[1,0]
	v_pk_mul_f32 v[4:5], v[4:5], v[0:1] op_sel_hi:[1,0]
	ds_write2_b32 v47, v2, v3 offset1:1
	ds_write2_b32 v47, v4, v5 offset0:2 offset1:3
	v_pk_mul_f32 v[2:3], v[6:7], v[46:47] op_sel_hi:[1,0]
	v_pk_mul_f32 v[4:5], v[8:9], v[46:47] op_sel_hi:[1,0]
	v_pk_mul_f32 v[6:7], v[14:15], v[48:49] op_sel_hi:[1,0]
	v_pk_mul_f32 v[8:9], v[16:17], v[48:49] op_sel_hi:[1,0]
	v_pk_mul_f32 v[12:13], v[12:13], v[84:85] op_sel_hi:[1,0]
	v_pk_mul_f32 v[14:15], v[22:23], v[86:87] op_sel_hi:[1,0]
	v_pk_mul_f32 v[16:17], v[24:25], v[86:87] op_sel_hi:[1,0]
	v_pk_mul_f32 v[18:19], v[18:19], v[88:89] op_sel_hi:[1,0]
	v_pk_mul_f32 v[20:21], v[20:21], v[88:89] op_sel_hi:[1,0]
	v_pk_mul_f32 v[22:23], v[30:31], v[90:91] op_sel_hi:[1,0]
	v_pk_mul_f32 v[24:25], v[32:33], v[90:91] op_sel_hi:[1,0]
	v_pk_mul_f32 v[26:27], v[26:27], v[92:93] op_sel_hi:[1,0]
	v_pk_mul_f32 v[28:29], v[28:29], v[92:93] op_sel_hi:[1,0]
	ds_write2_b32 v85, v2, v3 offset1:1
	ds_write2_b32 v87, v4, v5 offset1:1
	ds_write2_b32 v89, v6, v7 offset1:1
	ds_write2_b32 v91, v8, v9 offset1:1
	ds_write2_b32 v93, v10, v11 offset1:1
	ds_write2_b32 v94, v12, v13 offset1:1
	ds_write2_b32 v49, v14, v15 offset1:1
	ds_write2_b32 v49, v16, v17 offset0:2 offset1:3
	ds_write2_b32 v95, v18, v19 offset1:1
	ds_write2_b32 v96, v20, v21 offset1:1
	ds_write2_b32 v97, v22, v23 offset1:1
	ds_write2_b32 v98, v24, v25 offset1:1
	ds_write2_b32 v99, v26, v27 offset1:1
	ds_write2_b32 v100, v28, v29 offset1:1
	s_waitcnt lgkmcnt(0)
	v_add_u32_e32 v4, s14, v64
	v_lshl_add_u64 v[2:3], v[40:41], 0, s[4:5]
	v_cmp_gt_i32_e32 vcc, s23, v4
	v_writelane_b32 v252, s1, 34
	s_and_saveexec_b64 s[0:1], vcc
	s_cbranch_execz .LBB0_674
	ds_read2_b32 v[6:7], v55 offset1:33
	ds_read2_b32 v[8:9], v55 offset0:66 offset1:99
	ds_read2_b32 v[10:11], v55 offset0:132 offset1:165
	ds_read2_b32 v[12:13], v55 offset0:198 offset1:231
	v_ashrrev_i32_e32 v5, 31, v4
	v_lshlrev_b64 v[4:5], 12, v[4:5]
	s_waitcnt lgkmcnt(0)
	v_cvt_pk_bf16_f32 v6, v6, v7
	v_cvt_pk_bf16_f32 v7, v8, v9
	v_cvt_pk_bf16_f32 v8, v10, v11
	v_cvt_pk_bf16_f32 v9, v12, v13
	v_lshl_add_u64 v[4:5], v[2:3], 0, v[4:5]
	global_store_dwordx4 v[4:5], v[6:9], off sc1
.LBB0_674:
	s_or_b64 exec, exec, s[0:1]
	v_add_u32_e32 v4, s14, v63
	v_cmp_gt_i32_e32 vcc, s23, v4
	s_and_saveexec_b64 s[0:1], vcc
	s_cbranch_execz .LBB0_676
	ds_read2_b32 v[6:7], v55 offset0:8 offset1:41
	ds_read2_b32 v[8:9], v55 offset0:74 offset1:107
	ds_read2_b32 v[10:11], v55 offset0:140 offset1:173
	ds_read2_b32 v[12:13], v55 offset0:206 offset1:239
	v_ashrrev_i32_e32 v5, 31, v4
	v_lshlrev_b64 v[4:5], 12, v[4:5]
	s_waitcnt lgkmcnt(0)
	v_cvt_pk_bf16_f32 v6, v6, v7
	v_cvt_pk_bf16_f32 v7, v8, v9
	v_cvt_pk_bf16_f32 v8, v10, v11
	v_cvt_pk_bf16_f32 v9, v12, v13
	v_lshl_add_u64 v[4:5], v[2:3], 0, v[4:5]
	global_store_dwordx4 v[4:5], v[6:9], off sc1
.LBB0_676:
	s_or_b64 exec, exec, s[0:1]
	v_add_u32_e32 v4, s14, v62
	v_cmp_gt_i32_e32 vcc, s23, v4
	s_and_saveexec_b64 s[0:1], vcc
	s_cbranch_execz .LBB0_678
	ds_read2_b32 v[6:7], v55 offset0:16 offset1:49
	ds_read2_b32 v[8:9], v55 offset0:82 offset1:115
	ds_read2_b32 v[10:11], v55 offset0:148 offset1:181
	ds_read2_b32 v[12:13], v55 offset0:214 offset1:247
	v_ashrrev_i32_e32 v5, 31, v4
	v_lshlrev_b64 v[4:5], 12, v[4:5]
	s_waitcnt lgkmcnt(0)
	v_cvt_pk_bf16_f32 v6, v6, v7
	v_cvt_pk_bf16_f32 v7, v8, v9
	v_cvt_pk_bf16_f32 v8, v10, v11
	v_cvt_pk_bf16_f32 v9, v12, v13
	v_lshl_add_u64 v[4:5], v[2:3], 0, v[4:5]
	global_store_dwordx4 v[4:5], v[6:9], off sc1
.LBB0_678:
	s_or_b64 exec, exec, s[0:1]
	v_add_u32_e32 v4, s14, v61
	v_cmp_gt_i32_e32 vcc, s23, v4
	s_and_saveexec_b64 s[0:1], vcc
	s_cbranch_execz .LBB0_680
	ds_read2_b32 v[6:7], v55 offset0:24 offset1:57
	ds_read2_b32 v[8:9], v55 offset0:90 offset1:123
	ds_read2_b32 v[10:11], v55 offset0:156 offset1:189
	ds_read2_b32 v[12:13], v55 offset0:222 offset1:255
	v_ashrrev_i32_e32 v5, 31, v4
	v_lshlrev_b64 v[4:5], 12, v[4:5]
	s_waitcnt lgkmcnt(0)
	v_cvt_pk_bf16_f32 v6, v6, v7
	v_cvt_pk_bf16_f32 v7, v8, v9
	v_cvt_pk_bf16_f32 v8, v10, v11
	v_cvt_pk_bf16_f32 v9, v12, v13
	v_lshl_add_u64 v[2:3], v[2:3], 0, v[4:5]
	global_store_dwordx4 v[2:3], v[6:9], off sc1

; #define LAS __attribute__((address_space(3)))
; __device__ __forceinline__ unsigned pk2(float lo, float hi) { const f32x2v v = {lo, hi}; return __builtin_bit_cast(unsigned, __builtin_convertvector(v, bf16x2v)); }
; __device__ __forceinline__ void tr_item(const float* W, int N, bf16_t* WT, int item, int lane, LAS float* scr, int fox, const float* gk) {
;     const int nblk = (N + 31) >> 5, kb = item / nblk, nb = item - kb * nblk, k0 = 64 * kb, n0 = 32 * nb;
;     const int nq = lane & 7, kr = lane >> 3, nc = n0 + 4 * nq;
;     f32x4 wv[8];
; #pragma unroll
;     for (int i = 0; i < 8; ++i) wv[i] = (nc < N) ? *(const f32x4*)(W + (size_t)(k0 + kr + 8 * i) * N + nc) : (f32x4){0.f, 0.f, 0.f, 0.f};
; #pragma unroll
;     for (int i = 0; i < 8; ++i) { const int kk = kr + 8 * i; const float gg = gk ? gk[k0 + kk] : 1.f;
; #pragma unroll
;         for (int e2 = 0; e2 < 4; ++e2) scr[kk * 33 + 4 * nq + e2] = wv[i][e2] * gg; }
;     asm volatile("s_waitcnt lgkmcnt(0)" ::: "memory");
;     const int c = lane & 7;
; #pragma unroll
;     for (int j = 0; j < 4; ++j) { const int nl = (lane >> 3) + 8 * j, n = n0 + nl; const LAS float* s = scr + (8 * c) * 33 + nl;
;         if (n < N) { int nd = n; if (fox) { if (n >= 4620) nd = n - 12; else if (n >= 4608) nd = n - 4608 + 7168; }
;             u32x4 o; o.x = pk2(s[0 * 33], s[1 * 33]); o.y = pk2(s[2 * 33], s[3 * 33]); o.z = pk2(s[4 * 33], s[5 * 33]); o.w = pk2(s[6 * 33], s[7 * 33]);
;             *(u32x4*)(WT + (size_t)nd * DM + k0 + 8 * c) = o; } }
;     asm volatile("s_waitcnt lgkmcnt(0)" ::: "memory");
.LBB0_699:
	s_or_b64 exec, exec, s[4:5]
	v_lshlrev_b32_e32 v0, 2, v48
	v_readlane_b32 s0, v252, 18
	v_or_b32_e32 v46, s15, v52
	v_or_b32_e32 v47, s15, v53
	v_or_b32_e32 v48, s15, v54
	v_readlane_b32 s1, v252, 19
	v_lshlrev_b32_e32 v46, 2, v46
	v_lshlrev_b32_e32 v47, 2, v47
	v_lshlrev_b32_e32 v49, 2, v48
	v_or_b32_e32 v48, s15, v56
	v_lshlrev_b32_e32 v85, 2, v48
	global_load_dword v0, v0, s[0:1]
	s_nop 0
	global_load_dword v46, v46, s[0:1]
	s_nop 0
	global_load_dword v48, v47, s[0:1]
	global_load_dword v84, v49, s[0:1]
	global_load_dword v86, v85, s[0:1]
	v_or_b32_e32 v47, s15, v58
	v_lshlrev_b32_e32 v47, 2, v47
	v_or_b32_e32 v49, s15, v59
	v_lshlrev_b32_e32 v49, 2, v49
	global_load_dword v88, v47, s[0:1]
	global_load_dword v90, v49, s[0:1]
	v_or_b32_e32 v47, s15, v60
	v_lshlrev_b32_e32 v47, 2, v47
	global_load_dword v92, v47, s[0:1]
	v_add_u32_e32 v47, v50, v51
	v_add_u32_e32 v49, v50, v57
	v_add_u32_e32 v85, 0x420, v47
	v_add_u32_e32 v87, 0x428, v47
	v_add_u32_e32 v89, 0x840, v47
	v_add_u32_e32 v91, 0x848, v47
	v_add_u32_e32 v93, 0xc60, v47
	v_readlane_b32 s0, v252, 33
	v_add_u32_e32 v94, 0xc68, v47
	v_add_u32_e32 v95, 0x420, v49
	v_add_u32_e32 v96, 0x428, v49
	v_add_u32_e32 v97, 0x840, v49
	v_add_u32_e32 v98, 0x848, v49
	v_add_u32_e32 v99, 0xc60, v49
	v_add_u32_e32 v100, 0xc68, v49
	v_readlane_b32 s1, v252, 34
	s_mov_b32 s5, s1
	v_writelane_b32 v252, s0, 33
	s_lshl_b32 s4, s15, 1
	s_waitcnt vmcnt(0)
	v_pk_mul_f32 v[10:11], v[10:11], v[84:85] op_sel_hi:[1,0]
	v_pk_mul_f32 v[2:3], v[2:3], v[0:1] op_sel_hi:[1,0]
	v_pk_mul_f32 v[4:5], v[4:5], v[0:1] op_sel_hi:[1,0]
	ds_write2_b32 v47, v2, v3 offset1:1
	ds_write2_b32 v47, v4, v5 offset0:2 offset1:3
	v_pk_mul_f32 v[2:3], v[6:7], v[46:47] op_sel_hi:[1,0]
	v_pk_mul_f32 v[4:5], v[8:9], v[46:47] op_sel_hi:[1,0]
	v_pk_mul_f32 v[6:7], v[14:15], v[48:49] op_sel_hi:[1,0]
	v_pk_mul_f32 v[8:9], v[16:17], v[48:49] op_sel_hi:[1,0]
	v_pk_mul_f32 v[12:13], v[12:13], v[84:85] op_sel_hi:[1,0]
	v_pk_mul_f32 v[14:15], v[22:23], v[86:87] op_sel_hi:[1,0]
	v_pk_mul_f32 v[16:17], v[24:25], v[86:87] op_sel_hi:[1,0]
	v_pk_mul_f32 v[18:19], v[18:19], v[88:89] op_sel_hi:[1,0]
	v_pk_mul_f32 v[20:21], v[20:21], v[88:89] op_sel_hi:[1,0]
	v_pk_mul_f32 v[22:23], v[30:31], v[90:91] op_sel_hi:[1,0]
	v_pk_mul_f32 v[24:25], v[32:33], v[90:91] op_sel_hi:[1,0]
	v_pk_mul_f32 v[26:27], v[26:27], v[92:93] op_sel_hi:[1,0]
	v_pk_mul_f32 v[28:29], v[28:29], v[92:93] op_sel_hi:[1,0]
	ds_write2_b32 v85, v2, v3 offset1:1
	ds_write2_b32 v87, v4, v5 offset1:1
	ds_write2_b32 v89, v6, v7 offset1:1
	ds_write2_b32 v91, v8, v9 offset1:1
	ds_write2_b32 v93, v10, v11 offset1:1
	ds_write2_b32 v94, v12, v13 offset1:1
	ds_write2_b32 v49, v14, v15 offset1:1
	ds_write2_b32 v49, v16, v17 offset0:2 offset1:3
	ds_write2_b32 v95, v18, v19 offset1:1
	ds_write2_b32 v96, v20, v21 offset1:1
	ds_write2_b32 v97, v22, v23 offset1:1
	ds_write2_b32 v98, v24, v25 offset1:1
	ds_write2_b32 v99, v26, v27 offset1:1
	ds_write2_b32 v100, v28, v29 offset1:1
	s_waitcnt lgkmcnt(0)
	v_writelane_b32 v252, s1, 34
	v_add_u32_e32 v4, s14, v69
	s_movk_i32 s0, 0x1c00
	v_lshl_add_u64 v[2:3], v[42:43], 0, s[4:5]
	v_cmp_gt_i32_e32 vcc, s0, v4
	s_and_saveexec_b64 s[0:1], vcc
	s_cbranch_execz .LBB0_701
	ds_read2_b32 v[6:7], v55 offset1:33
	ds_read2_b32 v[8:9], v55 offset0:66 offset1:99
	ds_read2_b32 v[10:11], v55 offset0:132 offset1:165
	ds_read2_b32 v[12:13], v55 offset0:198 offset1:231
	v_ashrrev_i32_e32 v5, 31, v4
	v_lshlrev_b64 v[4:5], 12, v[4:5]
	s_waitcnt lgkmcnt(0)
	v_cvt_pk_bf16_f32 v6, v6, v7
	v_cvt_pk_bf16_f32 v7, v8, v9
	v_cvt_pk_bf16_f32 v8, v10, v11
	v_cvt_pk_bf16_f32 v9, v12, v13
	v_lshl_add_u64 v[4:5], v[2:3], 0, v[4:5]
	global_store_dwordx4 v[4:5], v[6:9], off sc1
.LBB0_701:
	s_or_b64 exec, exec, s[0:1]
	v_add_u32_e32 v4, s14, v68
	s_movk_i32 s0, 0x1c00
	v_cmp_gt_i32_e32 vcc, s0, v4
	s_and_saveexec_b64 s[0:1], vcc
	s_cbranch_execz .LBB0_703
	ds_read2_b32 v[6:7], v55 offset0:8 offset1:41
	ds_read2_b32 v[8:9], v55 offset0:74 offset1:107
	ds_read2_b32 v[10:11], v55 offset0:140 offset1:173
	ds_read2_b32 v[12:13], v55 offset0:206 offset1:239
	v_ashrrev_i32_e32 v5, 31, v4
	v_lshlrev_b64 v[4:5], 12, v[4:5]
	s_waitcnt lgkmcnt(0)
	v_cvt_pk_bf16_f32 v6, v6, v7
	v_cvt_pk_bf16_f32 v7, v8, v9
	v_cvt_pk_bf16_f32 v8, v10, v11
	v_cvt_pk_bf16_f32 v9, v12, v13
	v_lshl_add_u64 v[4:5], v[2:3], 0, v[4:5]
	global_store_dwordx4 v[4:5], v[6:9], off sc1
.LBB0_703:
	s_or_b64 exec, exec, s[0:1]
	v_add_u32_e32 v4, s14, v67
	s_movk_i32 s0, 0x1c00
	v_cmp_gt_i32_e32 vcc, s0, v4
	s_and_saveexec_b64 s[0:1], vcc
	s_cbranch_execz .LBB0_705
	ds_read2_b32 v[6:7], v55 offset0:16 offset1:49
	ds_read2_b32 v[8:9], v55 offset0:82 offset1:115
	ds_read2_b32 v[10:11], v55 offset0:148 offset1:181
	ds_read2_b32 v[12:13], v55 offset0:214 offset1:247
	v_ashrrev_i32_e32 v5, 31, v4
	v_lshlrev_b64 v[4:5], 12, v[4:5]
	s_waitcnt lgkmcnt(0)
	v_cvt_pk_bf16_f32 v6, v6, v7
	v_cvt_pk_bf16_f32 v7, v8, v9
	v_cvt_pk_bf16_f32 v8, v10, v11
	v_cvt_pk_bf16_f32 v9, v12, v13
	v_lshl_add_u64 v[4:5], v[2:3], 0, v[4:5]
	global_store_dwordx4 v[4:5], v[6:9], off sc1
.LBB0_705:
	s_or_b64 exec, exec, s[0:1]
	v_add_u32_e32 v4, s14, v66
	s_movk_i32 s0, 0x1c00
	v_cmp_gt_i32_e32 vcc, s0, v4
	s_and_saveexec_b64 s[0:1], vcc
	s_cbranch_execz .LBB0_707
	ds_read2_b32 v[6:7], v55 offset0:24 offset1:57
	ds_read2_b32 v[8:9], v55 offset0:90 offset1:123
	ds_read2_b32 v[10:11], v55 offset0:156 offset1:189
	ds_read2_b32 v[12:13], v55 offset0:222 offset1:255
	v_ashrrev_i32_e32 v5, 31, v4
	v_lshlrev_b64 v[4:5], 12, v[4:5]
	s_waitcnt lgkmcnt(0)
	v_cvt_pk_bf16_f32 v6, v6, v7
	v_cvt_pk_bf16_f32 v7, v8, v9
	v_cvt_pk_bf16_f32 v8, v10, v11
	v_cvt_pk_bf16_f32 v9, v12, v13
	v_lshl_add_u64 v[2:3], v[2:3], 0, v[4:5]
	global_store_dwordx4 v[2:3], v[6:9], off sc1

; #define LAS __attribute__((address_space(3)))
; __device__ __forceinline__ unsigned pk2(float lo, float hi) { const f32x2v v = {lo, hi}; return __builtin_bit_cast(unsigned, __builtin_convertvector(v, bf16x2v)); }
; __device__ __forceinline__ void tr_item(const float* W, int N, bf16_t* WT, int item, int lane, LAS float* scr, int fox, const float* gk) {
;     const int nblk = (N + 31) >> 5, kb = item / nblk, nb = item - kb * nblk, k0 = 64 * kb, n0 = 32 * nb;
;     const int nq = lane & 7, kr = lane >> 3, nc = n0 + 4 * nq;
;     f32x4 wv[8];
; #pragma unroll
;     for (int i = 0; i < 8; ++i) wv[i] = (nc < N) ? *(const f32x4*)(W + (size_t)(k0 + kr + 8 * i) * N + nc) : (f32x4){0.f, 0.f, 0.f, 0.f};
; #pragma unroll
;     for (int i = 0; i < 8; ++i) { const int kk = kr + 8 * i; const float gg = gk ? gk[k0 + kk] : 1.f;
; #pragma unroll
;         for (int e2 = 0; e2 < 4; ++e2) scr[kk * 33 + 4 * nq + e2] = wv[i][e2] * gg; }
;     asm volatile("s_waitcnt lgkmcnt(0)" ::: "memory");
;     const int c = lane & 7;
; #pragma unroll
;     for (int j = 0; j < 4; ++j) { const int nl = (lane >> 3) + 8 * j, n = n0 + nl; const LAS float* s = scr + (8 * c) * 33 + nl;
;         if (n < N) { int nd = n; if (fox) { if (n >= 4620) nd = n - 12; else if (n >= 4608) nd = n - 4608 + 7168; }
;             u32x4 o; o.x = pk2(s[0 * 33], s[1 * 33]); o.y = pk2(s[2 * 33], s[3 * 33]); o.z = pk2(s[4 * 33], s[5 * 33]); o.w = pk2(s[6 * 33], s[7 * 33]);
;             *(u32x4*)(WT + (size_t)nd * DM + k0 + 8 * c) = o; } }
;     asm volatile("s_waitcnt lgkmcnt(0)" ::: "memory");
.LBB0_726:
	s_or_b64 exec, exec, s[4:5]
	v_lshlrev_b32_e32 v0, 2, v48
	v_readlane_b32 s0, v252, 20
	v_or_b32_e32 v46, s15, v52
	v_or_b32_e32 v47, s15, v53
	v_or_b32_e32 v48, s15, v54
	v_readlane_b32 s1, v252, 21
	v_lshlrev_b32_e32 v46, 2, v46
	v_lshlrev_b32_e32 v47, 2, v47
	v_lshlrev_b32_e32 v49, 2, v48
	v_or_b32_e32 v48, s15, v56
	v_lshlrev_b32_e32 v85, 2, v48
	global_load_dword v0, v0, s[0:1]
	s_nop 0
	global_load_dword v46, v46, s[0:1]
	s_nop 0
	global_load_dword v48, v47, s[0:1]
	global_load_dword v84, v49, s[0:1]
	global_load_dword v86, v85, s[0:1]
	v_or_b32_e32 v47, s15, v58
	v_lshlrev_b32_e32 v47, 2, v47
	v_or_b32_e32 v49, s15, v59
	v_lshlrev_b32_e32 v49, 2, v49
	global_load_dword v88, v47, s[0:1]
	global_load_dword v90, v49, s[0:1]
	v_or_b32_e32 v47, s15, v60
	v_lshlrev_b32_e32 v47, 2, v47
	global_load_dword v92, v47, s[0:1]
	v_add_u32_e32 v47, v50, v51
	v_add_u32_e32 v49, v50, v57
	v_add_u32_e32 v85, 0x420, v47
	v_add_u32_e32 v87, 0x428, v47
	v_add_u32_e32 v89, 0x840, v47
	v_add_u32_e32 v91, 0x848, v47
	v_add_u32_e32 v93, 0xc60, v47
	v_readlane_b32 s0, v252, 33
	v_add_u32_e32 v94, 0xc68, v47
	v_add_u32_e32 v95, 0x420, v49
	v_add_u32_e32 v96, 0x428, v49
	v_add_u32_e32 v97, 0x840, v49
	v_add_u32_e32 v98, 0x848, v49
	v_add_u32_e32 v99, 0xc60, v49
	v_add_u32_e32 v100, 0xc68, v49
	v_readlane_b32 s1, v252, 34
	s_mov_b32 s5, s1
	v_writelane_b32 v252, s0, 33
	s_lshl_b32 s4, s15, 1
	s_waitcnt vmcnt(0)
	v_pk_mul_f32 v[2:3], v[2:3], v[46:47] op_sel_hi:[1,0]
	v_pk_mul_f32 v[4:5], v[4:5], v[46:47] op_sel_hi:[1,0]
	v_pk_mul_f32 v[6:7], v[6:7], v[0:1] op_sel_hi:[1,0]
	v_pk_mul_f32 v[8:9], v[8:9], v[0:1] op_sel_hi:[1,0]
	ds_write2_b32 v47, v6, v7 offset1:1
	ds_write2_b32 v47, v8, v9 offset0:2 offset1:3
	v_pk_mul_f32 v[6:7], v[14:15], v[48:49] op_sel_hi:[1,0]
	v_pk_mul_f32 v[8:9], v[16:17], v[48:49] op_sel_hi:[1,0]
	v_pk_mul_f32 v[10:11], v[10:11], v[84:85] op_sel_hi:[1,0]
	v_pk_mul_f32 v[12:13], v[12:13], v[84:85] op_sel_hi:[1,0]
	v_pk_mul_f32 v[14:15], v[22:23], v[86:87] op_sel_hi:[1,0]
	v_pk_mul_f32 v[16:17], v[24:25], v[86:87] op_sel_hi:[1,0]
	v_pk_mul_f32 v[18:19], v[18:19], v[88:89] op_sel_hi:[1,0]
	v_pk_mul_f32 v[20:21], v[20:21], v[88:89] op_sel_hi:[1,0]
	v_pk_mul_f32 v[22:23], v[30:31], v[90:91] op_sel_hi:[1,0]
	v_pk_mul_f32 v[24:25], v[32:33], v[90:91] op_sel_hi:[1,0]
	v_pk_mul_f32 v[26:27], v[26:27], v[92:93] op_sel_hi:[1,0]
	v_pk_mul_f32 v[28:29], v[28:29], v[92:93] op_sel_hi:[1,0]
	ds_write2_b32 v85, v2, v3 offset1:1
	ds_write2_b32 v87, v4, v5 offset1:1
	ds_write2_b32 v89, v6, v7 offset1:1
	ds_write2_b32 v91, v8, v9 offset1:1
	ds_write2_b32 v93, v10, v11 offset1:1
	ds_write2_b32 v94, v12, v13 offset1:1
	ds_write2_b32 v49, v14, v15 offset1:1
	ds_write2_b32 v49, v16, v17 offset0:2 offset1:3
	ds_write2_b32 v95, v18, v19 offset1:1
	ds_write2_b32 v96, v20, v21 offset1:1
	ds_write2_b32 v97, v22, v23 offset1:1
	ds_write2_b32 v98, v24, v25 offset1:1
	ds_write2_b32 v99, v26, v27 offset1:1
	ds_write2_b32 v100, v28, v29 offset1:1
	s_waitcnt lgkmcnt(0)
	v_writelane_b32 v252, s1, 34
	v_add_u32_e32 v0, s14, v80
	s_movk_i32 s0, 0x1c0c
	v_lshl_add_u64 v[2:3], v[44:45], 0, s[4:5]
	v_cmp_gt_i32_e32 vcc, s0, v0
	s_and_saveexec_b64 s[0:1], vcc
	s_cbranch_execz .LBB0_728
	s_movk_i32 s4, 0x11ff
	v_add_u32_e32 v4, s14, v82
	v_cmp_lt_i32_e32 vcc, s4, v0
	s_movk_i32 s4, 0x120b
	v_add_u32_e32 v12, s14, v81
	v_cndmask_b32_e32 v13, v0, v4, vcc
	ds_read2_b32 v[4:5], v55 offset1:33
	ds_read2_b32 v[6:7], v55 offset0:66 offset1:99
	ds_read2_b32 v[8:9], v55 offset0:132 offset1:165
	ds_read2_b32 v[10:11], v55 offset0:198 offset1:231
	v_cmp_lt_i32_e32 vcc, s4, v0
	s_waitcnt lgkmcnt(0)
	v_cvt_pk_bf16_f32 v4, v4, v5
	v_cvt_pk_bf16_f32 v5, v6, v7
	v_cndmask_b32_e32 v12, v13, v12, vcc
	v_ashrrev_i32_e32 v13, 31, v12
	v_cvt_pk_bf16_f32 v6, v8, v9
	v_lshlrev_b64 v[8:9], 12, v[12:13]
	v_cvt_pk_bf16_f32 v7, v10, v11
	v_lshl_add_u64 v[8:9], v[2:3], 0, v[8:9]
	global_store_dwordx4 v[8:9], v[4:7], off sc1
.LBB0_728:
	s_or_b64 exec, exec, s[0:1]
	v_add_u32_e32 v0, s14, v77
	s_movk_i32 s0, 0x1c0c
	v_cmp_gt_i32_e32 vcc, s0, v0
	s_and_saveexec_b64 s[0:1], vcc
	s_cbranch_execz .LBB0_730
	s_movk_i32 s4, 0x11ff
	v_add_u32_e32 v4, s14, v79
	v_cmp_lt_i32_e32 vcc, s4, v0
	s_movk_i32 s4, 0x120b
	v_add_u32_e32 v12, s14, v78
	v_cndmask_b32_e32 v13, v0, v4, vcc
	ds_read2_b32 v[4:5], v55 offset0:8 offset1:41
	ds_read2_b32 v[6:7], v55 offset0:74 offset1:107
	ds_read2_b32 v[8:9], v55 offset0:140 offset1:173
	ds_read2_b32 v[10:11], v55 offset0:206 offset1:239
	v_cmp_lt_i32_e32 vcc, s4, v0
	s_waitcnt lgkmcnt(0)
	v_cvt_pk_bf16_f32 v4, v4, v5
	v_cvt_pk_bf16_f32 v5, v6, v7
	v_cndmask_b32_e32 v12, v13, v12, vcc
	v_ashrrev_i32_e32 v13, 31, v12
	v_cvt_pk_bf16_f32 v6, v8, v9
	v_lshlrev_b64 v[8:9], 12, v[12:13]
	v_cvt_pk_bf16_f32 v7, v10, v11
	v_lshl_add_u64 v[8:9], v[2:3], 0, v[8:9]
	global_store_dwordx4 v[8:9], v[4:7], off sc1
.LBB0_730:
	s_or_b64 exec, exec, s[0:1]
	v_add_u32_e32 v0, s14, v74
	s_movk_i32 s0, 0x1c0c
	v_cmp_gt_i32_e32 vcc, s0, v0
	s_and_saveexec_b64 s[0:1], vcc
	s_cbranch_execz .LBB0_732
	s_movk_i32 s4, 0x11ff
	v_add_u32_e32 v4, s14, v76
	v_cmp_lt_i32_e32 vcc, s4, v0
	s_movk_i32 s4, 0x120b
	v_add_u32_e32 v12, s14, v75
	v_cndmask_b32_e32 v13, v0, v4, vcc
	ds_read2_b32 v[4:5], v55 offset0:16 offset1:49
	ds_read2_b32 v[6:7], v55 offset0:82 offset1:115
	ds_read2_b32 v[8:9], v55 offset0:148 offset1:181
	ds_read2_b32 v[10:11], v55 offset0:214 offset1:247
	v_cmp_lt_i32_e32 vcc, s4, v0
	s_waitcnt lgkmcnt(0)
	v_cvt_pk_bf16_f32 v4, v4, v5
	v_cvt_pk_bf16_f32 v5, v6, v7
	v_cndmask_b32_e32 v12, v13, v12, vcc
	v_ashrrev_i32_e32 v13, 31, v12
	v_cvt_pk_bf16_f32 v6, v8, v9
	v_lshlrev_b64 v[8:9], 12, v[12:13]
	v_cvt_pk_bf16_f32 v7, v10, v11
	v_lshl_add_u64 v[8:9], v[2:3], 0, v[8:9]
	global_store_dwordx4 v[8:9], v[4:7], off sc1
.LBB0_732:
	s_or_b64 exec, exec, s[0:1]
	v_add_u32_e32 v0, s14, v71
	s_movk_i32 s0, 0x1c0c
	v_cmp_gt_i32_e32 vcc, s0, v0
	s_and_saveexec_b64 s[0:1], vcc
	s_cbranch_execz .LBB0_734
	s_movk_i32 s4, 0x11ff
	v_add_u32_e32 v4, s14, v73
	v_cmp_lt_i32_e32 vcc, s4, v0
	s_movk_i32 s4, 0x120b
	v_add_u32_e32 v12, s14, v72
	v_cndmask_b32_e32 v13, v0, v4, vcc
	ds_read2_b32 v[4:5], v55 offset0:24 offset1:57
	ds_read2_b32 v[6:7], v55 offset0:90 offset1:123
	ds_read2_b32 v[8:9], v55 offset0:156 offset1:189
	ds_read2_b32 v[10:11], v55 offset0:222 offset1:255
	v_cmp_lt_i32_e32 vcc, s4, v0
	s_waitcnt lgkmcnt(0)
	v_cvt_pk_bf16_f32 v4, v4, v5
	v_cvt_pk_bf16_f32 v5, v6, v7
	v_cndmask_b32_e32 v12, v13, v12, vcc
	v_ashrrev_i32_e32 v13, 31, v12
	v_cvt_pk_bf16_f32 v6, v8, v9
	v_lshlrev_b64 v[8:9], 12, v[12:13]
	v_cvt_pk_bf16_f32 v7, v10, v11
	v_lshl_add_u64 v[2:3], v[2:3], 0, v[8:9]
	global_store_dwordx4 v[2:3], v[4:7], off sc1

; #define LAS __attribute__((address_space(3)))
; __device__ __forceinline__ unsigned pk2(float lo, float hi) { const f32x2v v = {lo, hi}; return __builtin_bit_cast(unsigned, __builtin_convertvector(v, bf16x2v)); }
; __device__ __forceinline__ void tr_item(const float* W, int N, bf16_t* WT, int item, int lane, LAS float* scr, int fox, const float* gk) {
;     const int nblk = (N + 31) >> 5, kb = item / nblk, nb = item - kb * nblk, k0 = 64 * kb, n0 = 32 * nb;
;     const int nq = lane & 7, kr = lane >> 3, nc = n0 + 4 * nq;
;     f32x4 wv[8];
; #pragma unroll
;     for (int i = 0; i < 8; ++i) wv[i] = (nc < N) ? *(const f32x4*)(W + (size_t)(k0 + kr + 8 * i) * N + nc) : (f32x4){0.f, 0.f, 0.f, 0.f};
; #pragma unroll
;     for (int i = 0; i < 8; ++i) { const int kk = kr + 8 * i; const float gg = gk ? gk[k0 + kk] : 1.f;
; #pragma unroll
;         for (int e2 = 0; e2 < 4; ++e2) scr[kk * 33 + 4 * nq + e2] = wv[i][e2] * gg; }
;     asm volatile("s_waitcnt lgkmcnt(0)" ::: "memory");
;     const int c = lane & 7;
; #pragma unroll
;     for (int j = 0; j < 4; ++j) { const int nl = (lane >> 3) + 8 * j, n = n0 + nl; const LAS float* s = scr + (8 * c) * 33 + nl;
;         if (n < N) { int nd = n; if (fox) { if (n >= 4620) nd = n - 12; else if (n >= 4608) nd = n - 4608 + 7168; }
;             u32x4 o; o.x = pk2(s[0 * 33], s[1 * 33]); o.y = pk2(s[2 * 33], s[3 * 33]); o.z = pk2(s[4 * 33], s[5 * 33]); o.w = pk2(s[6 * 33], s[7 * 33]);
;             *(u32x4*)(WT + (size_t)nd * DM + k0 + 8 * c) = o; } }
;     asm volatile("s_waitcnt lgkmcnt(0)" ::: "memory");
.LBB0_764:
	v_add_u32_e32 v6, 0x840, v14
	ds_write2_b32 v6, v12, v13 offset1:1
	v_add_u32_e32 v6, 0x848, v14
	ds_write2_b32 v6, v10, v11 offset1:1
	v_pk_mul_f32 v[2:3], v[2:3], v[0:1] op_sel_hi:[1,0]
	v_add_u32_e32 v6, 0xc60, v14
	ds_write2_b32 v6, v2, v3 offset1:1
	v_pk_mul_f32 v[2:3], v[4:5], v[0:1] op_sel_hi:[1,0]
	v_add_u32_e32 v0, 0xc68, v14
	ds_write2_b32 v0, v2, v3 offset1:1
	s_waitcnt lgkmcnt(0)
	v_add_u32_e32 v4, s13, v34
	v_lshl_add_u64 v[2:3], s[4:5], 1, v[38:39]
	v_cmp_gt_i32_e32 vcc, s23, v4
	s_and_saveexec_b64 s[0:1], vcc
	s_cbranch_execz .LBB0_766
	ds_read2_b32 v[6:7], v55 offset1:33
	ds_read2_b32 v[8:9], v55 offset0:66 offset1:99
	ds_read2_b32 v[10:11], v55 offset0:132 offset1:165
	ds_read2_b32 v[12:13], v55 offset0:198 offset1:231
	v_ashrrev_i32_e32 v5, 31, v4
	s_waitcnt lgkmcnt(0)
	v_cvt_pk_bf16_f32 v6, v6, v7
	v_cvt_pk_bf16_f32 v7, v8, v9
	v_cvt_pk_bf16_f32 v8, v10, v11
	v_lshlrev_b64 v[10:11], 12, v[4:5]
	v_cvt_pk_bf16_f32 v9, v12, v13
	v_lshl_add_u64 v[10:11], v[2:3], 0, v[10:11]
	global_store_dwordx4 v[10:11], v[6:9], off sc1
.LBB0_766:
	s_or_b64 exec, exec, s[0:1]
	s_nop 0
	v_add_u32_e32 v6, 8, v4
	v_cmp_gt_i32_e32 vcc, s23, v6
	s_and_saveexec_b64 s[0:1], vcc
	s_cbranch_execz .LBB0_768
	ds_read2_b32 v[8:9], v55 offset0:8 offset1:41
	ds_read2_b32 v[10:11], v55 offset0:74 offset1:107
	ds_read2_b32 v[12:13], v55 offset0:140 offset1:173
	ds_read2_b32 v[14:15], v55 offset0:206 offset1:239
	v_ashrrev_i32_e32 v7, 31, v6
	v_lshlrev_b64 v[6:7], 12, v[6:7]
	s_waitcnt lgkmcnt(0)
	v_cvt_pk_bf16_f32 v8, v8, v9
	v_cvt_pk_bf16_f32 v9, v10, v11
	v_cvt_pk_bf16_f32 v10, v12, v13
	v_cvt_pk_bf16_f32 v11, v14, v15
	v_lshl_add_u64 v[6:7], v[2:3], 0, v[6:7]
	global_store_dwordx4 v[6:7], v[8:11], off sc1
.LBB0_768:
	s_or_b64 exec, exec, s[0:1]
	v_add_u32_e32 v6, 16, v4
	v_cmp_gt_i32_e32 vcc, s23, v6
	s_and_saveexec_b64 s[0:1], vcc
	s_cbranch_execz .LBB0_770
	ds_read2_b32 v[8:9], v55 offset0:16 offset1:49
	ds_read2_b32 v[10:11], v55 offset0:82 offset1:115
	ds_read2_b32 v[12:13], v55 offset0:148 offset1:181
	ds_read2_b32 v[14:15], v55 offset0:214 offset1:247
	v_ashrrev_i32_e32 v7, 31, v6
	v_lshlrev_b64 v[6:7], 12, v[6:7]
	s_waitcnt lgkmcnt(0)
	v_cvt_pk_bf16_f32 v8, v8, v9
	v_cvt_pk_bf16_f32 v9, v10, v11
	v_cvt_pk_bf16_f32 v10, v12, v13
	v_cvt_pk_bf16_f32 v11, v14, v15
	v_lshl_add_u64 v[6:7], v[2:3], 0, v[6:7]
	global_store_dwordx4 v[6:7], v[8:11], off sc1
.LBB0_770:
	s_or_b64 exec, exec, s[0:1]
	v_add_u32_e32 v4, 24, v4
	v_cmp_gt_i32_e32 vcc, s23, v4
	s_and_saveexec_b64 s[0:1], vcc
	s_cbranch_execz .LBB0_644
	ds_read2_b32 v[6:7], v55 offset0:24 offset1:57
	ds_read2_b32 v[8:9], v55 offset0:90 offset1:123
	ds_read2_b32 v[10:11], v55 offset0:156 offset1:189
	ds_read2_b32 v[12:13], v55 offset0:222 offset1:255
	v_ashrrev_i32_e32 v5, 31, v4
	v_lshlrev_b64 v[4:5], 12, v[4:5]
	s_waitcnt lgkmcnt(0)
	v_cvt_pk_bf16_f32 v6, v6, v7
	v_cvt_pk_bf16_f32 v7, v8, v9
	v_cvt_pk_bf16_f32 v8, v10, v11
	v_cvt_pk_bf16_f32 v9, v12, v13
	v_lshl_add_u64 v[2:3], v[2:3], 0, v[4:5]
	global_store_dwordx4 v[2:3], v[6:9], off sc1
	s_branch .LBB0_644

; __global__ void __launch_bounds__(512) mk_fwd(Params P) {
;     ...
;             { u32x4* zp = (u32x4*)((bf16_t*)(ws + WS_WIN1) + (size_t)NSRC1 * DM); const int nz = (NZ1 - NSRC1) * DM / 8;
;               for (int i = blockIdx.x * 512 + tid; i < nz; i += G * 512) zp[i] = (u32x4){0u, 0u, 0u, 0u}; }
.LBB0_775:
	v_add_u32_e32 v0, s94, v0
	s_mov_b32 s7, 0xf3ff
	v_cmp_lt_i32_e32 vcc, s7, v0
	global_store_dwordx4 v[2:3], v[228:231], off sc1
	s_or_b64 s[4:5], vcc, s[4:5]
	v_lshl_add_u64 v[2:3], v[2:3], 0, s[30:31]
	s_andn2_b64 exec, exec, s[4:5]
	s_cbranch_execnz .LBB0_775

; __device__ __forceinline__ unsigned pk2(float lo, float hi) { const f32x2v v = {lo, hi}; return __builtin_bit_cast(unsigned, __builtin_convertvector(v, bf16x2v)); }
; __global__ void __launch_bounds__(512) mk_fwd(Params P) {
;     ...
;               for (int i = blockIdx.x * 512 + tid; i < 2 * 12 * 2048; i += G * 512) { const int hd = i >> 11, rem = i & 2047, t = rem >> 4, ch = rem & 15;
;                   const float* src = P.a_w_s + (size_t)hd * 16384 + t * 128 + 8 * ch;
;                   f32x4 a0 = *(const f32x4*)src, a1 = *(const f32x4*)(src + 4);
;                   if (t < 64 && ch >= 8) { a0 = (f32x4){0.f, 0.f, 0.f, 0.f}; a1 = a0; }
;                   u32x4 w; w.x = pk2(a0[0], a0[1]); w.y = pk2(a0[2], a0[3]); w.z = pk2(a1[0], a1[1]); w.w = pk2(a1[2], a1[3]);
;                   *(u32x4*)(wsb + (size_t)hd * 16384 + t * 128 + 8 * ch) = w; } }
.LBB0_778:
	v_ashrrev_i32_e32 v12, 11, v3
	v_ashrrev_i32_e32 v13, 31, v12
	v_bfe_u32 v14, v3, 4, 7
	v_lshlrev_b64 v[4:5], 16, v[12:13]
	v_lshlrev_b32_e32 v0, 9, v14
	v_lshl_add_u64 v[4:5], s[80:81], 0, v[4:5]
	v_lshl_add_u64 v[4:5], v[4:5], 0, v[0:1]
	v_lshlrev_b32_e32 v0, 2, v2
	v_lshl_add_u64 v[8:9], v[4:5], 0, v[0:1]
	global_load_dwordx4 v[4:7], v[8:9], off offset:16
	s_nop 0
	global_load_dwordx4 v[8:11], v[8:9], off
	v_lshlrev_b64 v[12:13], 15, v[12:13]
	v_cmp_gt_u32_e64 s[0:1], 64, v14
	v_lshl_add_u64 v[12:13], s[10:11], 0, v[12:13]
	v_lshlrev_b32_e32 v0, 8, v14
	v_add_u32_e32 v3, s94, v3
	s_mov_b32 s4, 0xbfff
	s_and_b64 s[0:1], s[0:1], vcc
	v_lshl_add_u64 v[12:13], v[12:13], 0, v[0:1]
	v_lshlrev_b32_e32 v0, 1, v2
	v_cmp_lt_i32_e64 s[4:5], s4, v3
	v_lshl_add_u64 v[12:13], v[12:13], 0, v[0:1]
	s_or_b64 s[12:13], s[4:5], s[12:13]
	s_waitcnt vmcnt(0)
	v_cndmask_b32_e64 v0, v7, 0, s[0:1]
	v_cndmask_b32_e64 v7, v6, 0, s[0:1]
	v_cndmask_b32_e64 v6, v5, 0, s[0:1]
	v_cndmask_b32_e64 v14, v4, 0, s[0:1]
	v_cndmask_b32_e64 v5, v11, 0, s[0:1]
	v_cndmask_b32_e64 v10, v10, 0, s[0:1]
	v_cndmask_b32_e64 v4, v9, 0, s[0:1]
	v_cndmask_b32_e64 v8, v8, 0, s[0:1]
	v_cvt_pk_bf16_f32 v4, v8, v4
	v_cvt_pk_bf16_f32 v5, v10, v5
	v_cvt_pk_bf16_f32 v6, v14, v6
	v_cvt_pk_bf16_f32 v7, v7, v0
	global_store_dwordx4 v[12:13], v[4:7], off sc1
	s_andn2_b64 exec, exec, s[12:13]
	s_cbranch_execnz .LBB0_778

; __device__ __forceinline__ unsigned pk2(float lo, float hi) { const f32x2v v = {lo, hi}; return __builtin_bit_cast(unsigned, __builtin_convertvector(v, bf16x2v)); }
; __device__ __forceinline__ void rms_row_to_bf16(const float* xrow, const float* g, bf16_t* orow, int lane) {
;     const f32x4* xr = (const f32x4*)xrow + lane; const f32x4* gr = (const f32x4*)g + lane;
;     f32x4 v[8]; float s = 0.f;
; #pragma unroll
;     for (int j = 0; j < 8; ++j) { v[j] = xr[64 * j]; s += (v[j][0] * v[j][0] + v[j][1] * v[j][1]) + (v[j][2] * v[j][2] + v[j][3] * v[j][3]); }
;     const float rstd = rsqrtf(wave_sum(s) * (1.f / DM) + EPS);
;     u32x2* o8 = (u32x2*)orow + lane;
; #pragma unroll
;     for (int j = 0; j < 8; ++j) { const f32x4 gg = gr[64 * j]; u32x2 w; w.x = pk2(v[j][0] * rstd * gg[0], v[j][1] * rstd * gg[1]); w.y = pk2(v[j][2] * rstd * gg[2], v[j][3] * rstd * gg[3]); o8[64 * j] = w; }
; }
.LBB0_786:
	v_add_co_u32_e32 v2, vcc, 0xfffff000, v32
	global_load_dwordx4 v[6:9], v[32:33], off offset:-3072
	global_load_dwordx4 v[14:17], v[32:33], off offset:-2048
	global_load_dwordx4 v[10:13], v[32:33], off offset:-1024
	global_load_dwordx4 v[40:43], v[32:33], off offset:-4096
	v_addc_co_u32_e32 v3, vcc, -1, v33, vcc
	global_load_dwordx4 v[44:47], v[2:3], off offset:-3072
	global_load_dwordx4 v[48:51], v[2:3], off offset:-2048
	global_load_dwordx4 v[52:55], v[2:3], off offset:-1024
	s_nop 0
	global_load_dwordx4 v[2:5], v[32:33], off
	global_load_dwordx4 v[56:59], v[20:21], off
	s_add_i32 s0, s0, s28
	s_cmpk_gt_i32 s0, 0x7ff
	v_lshl_add_u64 v[32:33], v[32:33], 0, s[38:39]
	s_waitcnt vmcnt(0)
	v_mul_f32_e32 v72, v8, v8
	v_pk_mul_f32 v[60:61], v[16:17], v[16:17]
	v_pk_mul_f32 v[62:63], v[14:15], v[14:15]
	v_mul_f32_e32 v0, v11, v11
	v_mul_f32_e32 v64, v13, v13
	v_mul_f32_e32 v66, v41, v41
	v_mul_f32_e32 v68, v43, v43
	v_mul_f32_e32 v73, v9, v9
	v_mul_f32_e32 v74, v4, v4
	v_mul_f32_e32 v75, v5, v5
	v_pk_mov_b32 v[70:71], v[62:63], v[60:61] op_sel:[1,0]
	v_mov_b32_e32 v63, v61
	v_pk_fma_f32 v[60:61], v[10:11], v[10:11], v[0:1] op_sel_hi:[1,1,0]
	v_pk_fma_f32 v[64:65], v[12:13], v[12:13], v[64:65] op_sel_hi:[1,1,0]
	v_pk_fma_f32 v[66:67], v[40:41], v[40:41], v[66:67] op_sel_hi:[1,1,0]
	v_pk_fma_f32 v[68:69], v[42:43], v[42:43], v[68:69] op_sel_hi:[1,1,0]
	v_mov_b32_e32 v61, v74
	v_mov_b32_e32 v65, v75
	v_mov_b32_e32 v67, v72
	v_mov_b32_e32 v69, v73
	v_mov_b32_e32 v72, v45
	v_mov_b32_e32 v73, v49
	v_mov_b32_e32 v76, v47
	v_mov_b32_e32 v77, v51
	v_pk_add_f32 v[62:63], v[70:71], v[62:63]
	v_mov_b32_e32 v70, v44
	v_mov_b32_e32 v71, v48
	v_mov_b32_e32 v74, v46
	v_mov_b32_e32 v75, v50
	v_pk_mul_f32 v[78:79], v[54:55], v[54:55]
	v_pk_mul_f32 v[80:81], v[52:53], v[52:53]
	v_pk_add_f32 v[60:61], v[60:61], v[64:65]
	v_pk_add_f32 v[64:65], v[66:67], v[68:69]
	v_pk_mul_f32 v[66:67], v[72:73], v[72:73]
	v_pk_mul_f32 v[68:69], v[76:77], v[76:77]
	v_pk_mov_b32 v[72:73], v[80:81], v[78:79] op_sel:[1,0]
	v_mov_b32_e32 v81, v79
	v_pk_fma_f32 v[66:67], v[70:71], v[70:71], v[66:67]
	v_pk_fma_f32 v[68:69], v[74:75], v[74:75], v[68:69]
	v_pk_add_f32 v[70:71], v[72:73], v[80:81]
	v_pk_add_f32 v[66:67], v[66:67], v[68:69]
	v_mul_f32_e32 v39, v6, v6
	v_mul_f32_e32 v82, v7, v7
	v_pk_add_f32 v[68:69], v[70:71], v[70:71] op_sel:[0,1] op_sel_hi:[1,0]
	v_pk_add_f32 v[66:67], v[66:67], v[66:67] op_sel:[0,1] op_sel_hi:[1,0]
	v_mov_b32_e32 v69, v82
	v_mov_b32_e32 v67, v39
	v_pk_add_f32 v[66:67], v[66:67], v[68:69]
	v_mul_f32_e32 v83, v2, v2
	v_pk_add_f32 v[64:65], v[66:67], v[64:65]
	v_mul_f32_e32 v84, v3, v3
	v_pk_add_f32 v[62:63], v[62:63], v[62:63] op_sel:[0,1] op_sel_hi:[1,0]
	v_pk_add_f32 v[64:65], v[64:65], v[64:65] op_sel:[0,1] op_sel_hi:[1,0]
	v_mov_b32_e32 v63, v84
	v_mov_b32_e32 v65, v83
	v_pk_add_f32 v[62:63], v[64:65], v[62:63]
	s_nop 0
	v_pk_add_f32 v[60:61], v[62:63], v[60:61]
	s_nop 0
	v_add_f32_e32 v0, v60, v61
	ds_bpermute_b32 v39, v19, v0
	s_waitcnt lgkmcnt(0)
	v_add_f32_e32 v0, v0, v39
	ds_bpermute_b32 v39, v34, v0
	s_waitcnt lgkmcnt(0)
	v_add_f32_e32 v0, v0, v39
	ds_bpermute_b32 v39, v35, v0
	s_waitcnt lgkmcnt(0)
	v_add_f32_e32 v0, v0, v39
	ds_bpermute_b32 v39, v36, v0
	s_waitcnt lgkmcnt(0)
	v_add_f32_e32 v0, v0, v39
	ds_bpermute_b32 v39, v37, v0
	s_waitcnt lgkmcnt(0)
	v_add_f32_e32 v0, v0, v39
	ds_bpermute_b32 v39, v38, v0
	s_waitcnt lgkmcnt(0)
	v_add_f32_e32 v0, v0, v39
	v_fmamk_f32 v0, v0, 0x3a000000, v205
	v_mul_f32_e32 v39, 0x4b800000, v0
	v_cmp_gt_f32_e32 vcc, s68, v0
	s_nop 1
	v_cndmask_b32_e32 v0, v0, v39, vcc
	v_rsq_f32_e32 v0, v0
	s_nop 0
	v_mul_f32_e32 v39, 0x45800000, v0
	v_cndmask_b32_e32 v0, v0, v39, vcc
	v_pk_mul_f32 v[44:45], v[44:45], v[0:1] op_sel_hi:[1,0]
	v_pk_mul_f32 v[46:47], v[46:47], v[0:1] op_sel_hi:[1,0]
	v_pk_mul_f32 v[44:45], v[56:57], v[44:45]
	v_pk_mul_f32 v[46:47], v[58:59], v[46:47]
	v_cvt_pk_bf16_f32 v44, v44, v45
	v_cvt_pk_bf16_f32 v45, v46, v47
	global_store_dwordx2 v[30:31], v[44:45], off sc1
	global_load_dwordx4 v[44:47], v[20:21], off offset:1024
	v_pk_mul_f32 v[48:49], v[48:49], v[0:1] op_sel_hi:[1,0]
	v_pk_mul_f32 v[50:51], v[50:51], v[0:1] op_sel_hi:[1,0]
	v_pk_mul_f32 v[40:41], v[40:41], v[0:1] op_sel_hi:[1,0]
	v_pk_mul_f32 v[42:43], v[42:43], v[0:1] op_sel_hi:[1,0]
	v_pk_mul_f32 v[6:7], v[6:7], v[0:1] op_sel_hi:[1,0]
	v_pk_mul_f32 v[8:9], v[8:9], v[0:1] op_sel_hi:[1,0]
	v_pk_mul_f32 v[14:15], v[14:15], v[0:1] op_sel_hi:[1,0]
	v_pk_mul_f32 v[16:17], v[16:17], v[0:1] op_sel_hi:[1,0]
	v_pk_mul_f32 v[10:11], v[10:11], v[0:1] op_sel_hi:[1,0]
	v_pk_mul_f32 v[12:13], v[12:13], v[0:1] op_sel_hi:[1,0]
	v_pk_mul_f32 v[2:3], v[2:3], v[0:1] op_sel_hi:[1,0]
	v_pk_mul_f32 v[4:5], v[4:5], v[0:1] op_sel_hi:[1,0]
	s_waitcnt vmcnt(0)
	v_pk_mul_f32 v[44:45], v[44:45], v[48:49]
	v_pk_mul_f32 v[46:47], v[46:47], v[50:51]
	v_cvt_pk_bf16_f32 v44, v44, v45
	v_cvt_pk_bf16_f32 v45, v46, v47
	global_store_dwordx2 v[30:31], v[44:45], off offset:512 sc1
	global_load_dwordx4 v[44:47], v[20:21], off offset:2048
	v_pk_mul_f32 v[48:49], v[52:53], v[0:1] op_sel_hi:[1,0]
	v_pk_mul_f32 v[50:51], v[54:55], v[0:1] op_sel_hi:[1,0]
	s_waitcnt vmcnt(0)
	v_pk_mul_f32 v[44:45], v[44:45], v[48:49]
	v_pk_mul_f32 v[46:47], v[46:47], v[50:51]
	v_cvt_pk_bf16_f32 v44, v44, v45
	v_cvt_pk_bf16_f32 v45, v46, v47
	global_store_dwordx2 v[30:31], v[44:45], off offset:1024 sc1
	global_load_dwordx4 v[44:47], v[20:21], off offset:3072
	s_waitcnt vmcnt(0)
	v_pk_mul_f32 v[40:41], v[44:45], v[40:41]
	v_pk_mul_f32 v[42:43], v[46:47], v[42:43]
	v_cvt_pk_bf16_f32 v40, v40, v41
	v_cvt_pk_bf16_f32 v41, v42, v43
	global_store_dwordx2 v[30:31], v[40:41], off offset:1536 sc1
	global_load_dwordx4 v[40:43], v[22:23], off
	s_waitcnt vmcnt(0)
	v_pk_mul_f32 v[6:7], v[40:41], v[6:7]
	v_pk_mul_f32 v[8:9], v[42:43], v[8:9]
	v_cvt_pk_bf16_f32 v6, v6, v7
	v_cvt_pk_bf16_f32 v7, v8, v9
	global_store_dwordx2 v[30:31], v[6:7], off offset:2048 sc1
	global_load_dwordx4 v[6:9], v[24:25], off
	s_waitcnt vmcnt(0)
	v_pk_mul_f32 v[6:7], v[14:15], v[6:7]
	v_pk_mul_f32 v[8:9], v[16:17], v[8:9]
	v_cvt_pk_bf16_f32 v6, v6, v7
	v_cvt_pk_bf16_f32 v7, v8, v9
	global_store_dwordx2 v[30:31], v[6:7], off offset:2560 sc1
	global_load_dwordx4 v[6:9], v[26:27], off
	s_waitcnt vmcnt(0)
	v_pk_mul_f32 v[6:7], v[10:11], v[6:7]
	v_pk_mul_f32 v[8:9], v[12:13], v[8:9]
	v_cvt_pk_bf16_f32 v6, v6, v7
	v_cvt_pk_bf16_f32 v7, v8, v9
	global_store_dwordx2 v[30:31], v[6:7], off offset:3072 sc1
	global_load_dwordx4 v[6:9], v[28:29], off
	s_waitcnt vmcnt(0)
	v_pk_mul_f32 v[2:3], v[2:3], v[6:7]
	v_pk_mul_f32 v[4:5], v[4:5], v[8:9]
	v_cvt_pk_bf16_f32 v2, v2, v3
	v_cvt_pk_bf16_f32 v3, v4, v5
	global_store_dwordx2 v[30:31], v[2:3], off offset:3584 sc1
	v_lshl_add_u64 v[30:31], v[30:31], 0, s[54:55]
	s_cbranch_scc0 .LBB0_786

; __device__ __forceinline__ unsigned pk2(float lo, float hi) { const f32x2v v = {lo, hi}; return __builtin_bit_cast(unsigned, __builtin_convertvector(v, bf16x2v)); }
; __device__ __forceinline__ void row_to_bf16_ssq(const float* xrow, bf16_t* orow, float* ssq, int lane) {
;     const f32x4* xr = (const f32x4*)xrow + lane; u32x2* o8 = (u32x2*)orow + lane; float s = 0.f;
; #pragma unroll
;     for (int j = 0; j < 8; ++j) { const f32x4 v = xr[64 * j]; s += (v[0] * v[0] + v[1] * v[1]) + (v[2] * v[2] + v[3] * v[3]);
;         u32x2 w; w.x = pk2(v[0], v[1]); w.y = pk2(v[2], v[3]); o8[64 * j] = w; }
;     s = wave_sum(s);
;     if (lane == 0) *ssq = s;
; }
.LBB0_790:
	v_add_co_u32_e32 v16, vcc, 0xfffff000, v4
	v_lshl_add_u64 v[20:21], s[24:25], 0, v[2:3]
	s_nop 0
	v_addc_co_u32_e32 v17, vcc, -1, v5, vcc
	s_waitcnt lgkmcnt(0)
	global_load_dwordx4 v[12:15], v[16:17], off offset:-3072
	s_mov_b32 s4, 0xb100000
	v_add_co_u32_e32 v48, vcc, s4, v20
	s_waitcnt vmcnt(0)
	v_cvt_pk_bf16_f32 v20, v12, v13
	v_addc_co_u32_e32 v49, vcc, 0, v21, vcc
	v_cvt_pk_bf16_f32 v21, v14, v15
	global_store_dwordx2 v[48:49], v[20:21], off sc1
	global_load_dwordx4 v[20:23], v[16:17], off offset:-2048
	v_mul_f32_e32 v0, v13, v13
	v_mul_f32_e32 v13, v15, v15
	v_fmac_f32_e32 v0, v12, v12
	v_fmac_f32_e32 v13, v14, v14
	v_add_f32_e32 v0, v0, v13
	s_waitcnt vmcnt(0)
	v_cvt_pk_bf16_f32 v24, v20, v21
	v_cvt_pk_bf16_f32 v25, v22, v23
	global_store_dwordx2 v[48:49], v[24:25], off offset:512 sc1
	global_load_dwordx4 v[24:27], v[16:17], off offset:-1024
	v_mul_f32_e32 v12, v21, v21
	v_mul_f32_e32 v13, v23, v23
	v_fmac_f32_e32 v12, v20, v20
	v_fmac_f32_e32 v13, v22, v22
	v_add_f32_e32 v12, v12, v13
	v_add_f32_e32 v0, v0, v12
	s_waitcnt vmcnt(0)
	v_cvt_pk_bf16_f32 v16, v24, v25
	v_cvt_pk_bf16_f32 v17, v26, v27
	global_store_dwordx2 v[48:49], v[16:17], off offset:1024 sc1
	global_load_dwordx4 v[28:31], v[4:5], off offset:-4096
	v_mul_f32_e32 v12, v25, v25
	v_mul_f32_e32 v13, v27, v27
	v_fmac_f32_e32 v12, v24, v24
	v_fmac_f32_e32 v13, v26, v26
	v_add_f32_e32 v12, v12, v13
	v_add_f32_e32 v0, v0, v12
	s_waitcnt vmcnt(0)
	v_cvt_pk_bf16_f32 v16, v28, v29
	v_cvt_pk_bf16_f32 v17, v30, v31
	global_store_dwordx2 v[48:49], v[16:17], off offset:1536 sc1
	global_load_dwordx4 v[32:35], v[4:5], off offset:-3072
	v_mul_f32_e32 v12, v29, v29
	v_mul_f32_e32 v13, v31, v31
	v_fmac_f32_e32 v12, v28, v28
	v_fmac_f32_e32 v13, v30, v30
	v_add_f32_e32 v12, v12, v13
	v_add_f32_e32 v0, v0, v12
	s_waitcnt vmcnt(0)
	v_cvt_pk_bf16_f32 v16, v32, v33
	v_cvt_pk_bf16_f32 v17, v34, v35
	global_store_dwordx2 v[48:49], v[16:17], off offset:2048 sc1
	global_load_dwordx4 v[36:39], v[4:5], off offset:-2048
	v_mul_f32_e32 v12, v33, v33
	v_mul_f32_e32 v13, v35, v35
	v_fmac_f32_e32 v12, v32, v32
	v_fmac_f32_e32 v13, v34, v34
	v_add_f32_e32 v12, v12, v13
	v_add_f32_e32 v0, v0, v12
	s_waitcnt vmcnt(0)
	v_cvt_pk_bf16_f32 v16, v36, v37
	v_cvt_pk_bf16_f32 v17, v38, v39
	global_store_dwordx2 v[48:49], v[16:17], off offset:2560 sc1
	global_load_dwordx4 v[40:43], v[4:5], off offset:-1024
	v_mul_f32_e32 v12, v37, v37
	v_mul_f32_e32 v13, v39, v39
	v_fmac_f32_e32 v12, v36, v36
	v_fmac_f32_e32 v13, v38, v38
	v_add_f32_e32 v12, v12, v13
	v_add_f32_e32 v0, v0, v12
	s_waitcnt vmcnt(0)
	v_cvt_pk_bf16_f32 v16, v40, v41
	v_cvt_pk_bf16_f32 v17, v42, v43
	global_store_dwordx2 v[48:49], v[16:17], off offset:3072 sc1
	global_load_dwordx4 v[44:47], v[4:5], off
	v_mul_f32_e32 v12, v41, v41
	v_mul_f32_e32 v13, v43, v43
	v_fmac_f32_e32 v12, v40, v40
	v_fmac_f32_e32 v13, v42, v42
	v_add_f32_e32 v12, v12, v13
	v_add_f32_e32 v0, v0, v12
	s_waitcnt vmcnt(0)
	v_mul_f32_e32 v12, v45, v45
	v_mul_f32_e32 v13, v47, v47
	v_fmac_f32_e32 v12, v44, v44
	v_fmac_f32_e32 v13, v46, v46
	v_add_f32_e32 v12, v12, v13
	v_add_f32_e32 v0, v0, v12
	ds_bpermute_b32 v12, v6, v0
	v_cvt_pk_bf16_f32 v14, v44, v45
	v_cvt_pk_bf16_f32 v15, v46, v47
	global_store_dwordx2 v[48:49], v[14:15], off offset:3584 sc1
	s_waitcnt lgkmcnt(0)
	v_add_f32_e32 v0, v0, v12
	ds_bpermute_b32 v12, v7, v0
	s_waitcnt lgkmcnt(0)
	v_add_f32_e32 v0, v0, v12
	ds_bpermute_b32 v12, v8, v0
	s_waitcnt lgkmcnt(0)
	v_add_f32_e32 v0, v0, v12
	ds_bpermute_b32 v12, v9, v0
	s_waitcnt lgkmcnt(0)
	v_add_f32_e32 v0, v0, v12
	ds_bpermute_b32 v12, v10, v0
	s_waitcnt lgkmcnt(0)
	v_add_f32_e32 v0, v0, v12
	ds_bpermute_b32 v12, v11, v0
	s_and_saveexec_b64 s[4:5], s[0:1]
	s_cbranch_execz .LBB0_789
	s_add_u32 s10, s24, s7
	s_addc_u32 s11, s25, s8
	s_waitcnt lgkmcnt(0)
	v_add_f32_e32 v0, v0, v12
	v_mov_b64_e32 v[12:13], s[10:11]
	global_store_dword v[12:13], v0, off
	s_branch .LBB0_789
